# baseline (speedup 1.0000x reference)
.LBB0_629:
	v_ashrrev_i32_e32 v41, 31, v40
	v_lshlrev_b64 v[18:19], 12, v[40:41]
	s_waitcnt lgkmcnt(2)
	v_lshl_add_u64 v[26:27], v[34:35], 0, v[18:19]
	s_waitcnt lgkmcnt(0)
	global_load_dwordx4 v[22:25], v[26:27], off nt
	global_load_dwordx4 v[30:33], v[26:27], off offset:1024 nt
	global_load_dwordx4 v[18:21], v[26:27], off offset:2048 nt
	s_nop 0
	global_load_dwordx4 v[26:29], v[26:27], off offset:3072 nt
	v_add_u32_e32 v38, s98, v40
	v_cmp_gt_i32_e64 s[4:5], s91, v38
	v_ashrrev_i32_e32 v39, 31, v38
	s_and_saveexec_b64 s[6:7], s[4:5]
	s_cbranch_execz .LBB0_631
	v_lshlrev_b64 v[2:3], 12, v[38:39]
	v_lshl_add_u64 v[2:3], v[34:35], 0, v[2:3]
	global_load_dwordx4 v[14:17], v[2:3], off nt
	global_load_dwordx4 v[10:13], v[2:3], off offset:1024 nt
	global_load_dwordx4 v[6:9], v[2:3], off offset:2048 nt
	s_nop 0
	global_load_dwordx4 v[2:5], v[2:3], off offset:3072 nt
